# combo7 = combo6 + mlA conv-weight table (3 loads) and vT staging (2 loads) issued together instead of one round trip per iteration
# baseline (speedup 1.0000x reference)
.LBB0_1345:
	s_movk_i32 s31, 0x2ff
	v_mov_b32_e32 v4, v10
	v_ashrrev_i32_e32 v5, 8, v4
	v_lshl_add_u32 v70, v5, 10, v2
	v_ashrrev_i32_e32 v71, 31, v70
	v_cmp_gt_i32_e32 vcc, 4, v5
	v_lshl_add_u64 v[70:71], v[70:71], 2, s[22:23]
	s_nop 0
	v_cndmask_b32_e32 v71, v1, v71, vcc
	v_cndmask_b32_e32 v70, v0, v70, vcc
	global_load_dword v76, v[70:71], off
	v_add_u32_e32 v4, 0x200, v10
	v_ashrrev_i32_e32 v5, 8, v4
	v_lshl_add_u32 v72, v5, 10, v2
	v_ashrrev_i32_e32 v73, 31, v72
	v_cmp_gt_i32_e32 vcc, 4, v5
	v_lshl_add_u64 v[72:73], v[72:73], 2, s[22:23]
	s_nop 0
	v_cndmask_b32_e32 v73, v1, v73, vcc
	v_cndmask_b32_e32 v72, v0, v72, vcc
	global_load_dword v77, v[72:73], off
	v_cmp_gt_u32_e32 vcc, 0x100, v10
	s_and_saveexec_b64 s[60:61], vcc
	v_add_u32_e32 v4, 0x400, v10
	v_ashrrev_i32_e32 v5, 8, v4
	v_lshl_add_u32 v74, v5, 10, v2
	v_ashrrev_i32_e32 v75, 31, v74
	v_cmp_gt_i32_e32 vcc, 4, v5
	v_lshl_add_u64 v[74:75], v[74:75], 2, s[22:23]
	s_nop 0
	v_cndmask_b32_e32 v75, v1, v75, vcc
	v_cndmask_b32_e32 v74, v0, v74, vcc
	global_load_dword v78, v[74:75], off
	s_waitcnt vmcnt(0)
	ds_write_b32 v11, v78 offset:4096
	s_or_b64 exec, exec, s[60:61]
	ds_write_b32 v11, v76
	ds_write_b32 v11, v77 offset:2048
	s_mov_b64 s[60:61], exec

.LBB0_1363:
	v_mov_b32_e32 v1, v10
	v_mov_b32_e32 v0, v60
	v_ashrrev_i32_e32 v2, 4, v1
	v_and_b32_e32 v3, 0x78, v0
	v_mul_lo_u32 v70, v2, s93
	v_add3_u32 v70, s4, v70, v3
	v_lshl_add_u32 v70, v70, 1, v64
	v_lshlrev_b32_e32 v2, 1, v2
	v_mul_u32_u24_e32 v3, 0x90, v3
	v_add3_u32 v71, 0, v2, v3
	global_load_dwordx4 v[72:75], v70, s[62:63]
	v_add_u32_e32 v1, 0x200, v10
	v_add_u32_e32 v0, 0x1000, v60
	v_ashrrev_i32_e32 v2, 4, v1
	v_and_b32_e32 v3, 0x78, v0
	v_mul_lo_u32 v76, v2, s93
	v_add3_u32 v76, s4, v76, v3
	v_lshl_add_u32 v76, v76, 1, v64
	v_lshlrev_b32_e32 v2, 1, v2
	v_mul_u32_u24_e32 v3, 0x90, v3
	v_add3_u32 v77, 0, v2, v3
	global_load_dwordx4 v[78:81], v76, s[62:63]
	s_waitcnt vmcnt(1)
	ds_write_b16 v71, v72
	ds_write_b16_d16_hi v71, v72 offset:144
	ds_write_b16 v71, v73 offset:288
	ds_write_b16_d16_hi v71, v73 offset:432
	ds_write_b16 v71, v74 offset:576
	ds_write_b16_d16_hi v71, v74 offset:720
	ds_write_b16 v71, v75 offset:864
	ds_write_b16_d16_hi v71, v75 offset:1008
	s_waitcnt vmcnt(0)
	ds_write_b16 v77, v78
	ds_write_b16_d16_hi v77, v78 offset:144
	ds_write_b16 v77, v79 offset:288
	ds_write_b16_d16_hi v77, v79 offset:432
	ds_write_b16 v77, v80 offset:576
	ds_write_b16_d16_hi v77, v80 offset:720
	ds_write_b16 v77, v81 offset:864
	ds_write_b16_d16_hi v77, v81 offset:1008
	s_mov_b64 s[60:61], exec
